# v19 plus prefetch of the NSA work-queue ticket atomic and DS index exchange
# speedup vs baseline: 1.0021x; 1.0021x over previous
; DI void nsa_block(const bf16_t* P1, const bf16_t* VT1, const bf16_t* KSF, const bf16_t* KC, const bf16_t* VCT, bf16_t* O, const unsigned* kmx, int b, int g, int t0b, int wave, int lane, unsigned char* lds) {
;     unsigned char* wl = lds + wave * WAVE_LDS; unsigned char* SB = lds + NS_BASE;
;     const int t0w = t0b + 8 * wave, tid = wave * 64 + lane;
;     const bool kst = wave < 4;
;     const int st_row = kst ? (tid >> 3) : ((tid - 256) >> 2), st_ch = kst ? (tid & 7) : ((tid - 256) & 3);
;     const int st_dst = kst ? st_row * 144 + st_ch * 16 : NS_VOFF + st_row * 80 + st_ch * 16;
;     u32x4 sreg = {0u, 0u, 0u, 0u};
;     float* impA = (float*)wl; float* impB = impA + 1024; unsigned long long* selm = (unsigned long long*)(wl + 8192);
;     const int r = lane & 31, hf = lane >> 5, tk = r >> 2, hh = r & 3, krow = krow_of(r);
;     const int t = t0w + tk, head = g * 4 + hh, tmax = t0w + 7;
;     const float slope2 = exp2f(-0.5f * (float)(head + 1)) * LOG2E;
;     const bf16_t* P1 = (const bf16_t*)(p.ws + WS_BIG); const bf16_t* VT1 = (const bf16_t*)(p.ws + WS_VT);
;     const bf16_t* KC = (const bf16_t*)(p.ws + WS_KC); const bf16_t* VCT = (const bf16_t*)(p.ws + WS_VCT); bf16_t* O = (bf16_t*)(p.ws + WS_XN);
;     unsigned* qctr = (unsigned*)(p.ws + WS_QCTR) + 8 + rep;
;     volatile unsigned* qidx = (volatile unsigned*)(lds + NS_BASE + 2 * NS_BUF);
;     for (;;) {
;         if (threadIdx.x == 0) qidx[0] = atomicAdd(qctr, 1u);
.LBB0_962:
	s_cmp_gt_i32 s82, 10
	s_cselect_b64 s[0:1], -1, 0
	s_cmp_lt_i32 s83, 11
	s_cselect_b64 s[2:3], -1, 0
	s_or_b64 s[0:1], s[0:1], s[2:3]
	s_and_b64 vcc, exec, s[0:1]
	s_cbranch_vccnz .LBB0_1134
	s_add_u32 s0, s80, 0x3200000
	s_addc_u32 s1, s81, 0
	v_writelane_b32 v246, s0, 37
	s_mov_b64 s[22:23], src_shared_base
	v_and_b32_e32 v141, 3, v177
	v_writelane_b32 v246, s1, 38
	s_add_u32 s0, s80, 0x3300000
	s_addc_u32 s1, s81, 0
	v_writelane_b32 v246, s0, 41
	v_lshlrev_b32_e32 v2, 4, v141
	s_movk_i32 s96, 0x1200
	v_writelane_b32 v246, s1, 42
	s_add_u32 s0, s80, 0x31ff620
	s_addc_u32 s1, s81, 0
	v_writelane_b32 v246, s0, 43
	v_lshlrev_b32_e32 v3, 1, v177
	v_lshrrev_b32_e32 v6, 1, v177
	v_writelane_b32 v246, s1, 44
	v_readlane_b32 s0, v247, 31
	v_readlane_b32 s1, v247, 32
	s_mov_b32 s2, s0
	s_mulk_i32 s0, 0x2200
	v_readlane_b32 s1, v247, 9
	s_add_i32 s51, s0, 0
	s_lshl_b32 s3, s2, 3
	s_and_b32 s0, s1, 0xffffffc0
	s_cmpk_gt_u32 s1, 0xff
	s_cselect_b64 s[34:35], -1, 0
	s_add_u32 s36, s80, 0x31fb180
	v_or_b32_e32 v0, s0, v176
	s_addc_u32 s37, s81, 0
	s_lshl_b32 s0, s2, 2
	s_add_i32 s0, s0, 0
	s_add_i32 s22, s0, 0x15c40
	s_add_i32 s95, 0, 0x11000
	v_ashrrev_i32_e32 v137, 3, v0
	v_add_u32_e32 v0, 0xffffff00, v0
	s_cmpk_lt_u32 s1, 0x100
	v_ashrrev_i32_e32 v4, 2, v0
	s_movk_i32 s1, 0x50
	s_waitcnt lgkmcnt(0)
	v_mul_lo_u32 v1, v4, s1
	s_movk_i32 s1, 0x90
	v_and_b32_e32 v0, 7, v177
	v_add3_u32 v1, v1, v2, s96
	v_mul_lo_u32 v2, v137, s1
	v_and_b32_e32 v3, 8, v3
	v_and_b32_e32 v7, 19, v177
	v_and_b32_e32 v6, 4, v6
	s_cselect_b64 s[8:9], -1, 0
	v_lshl_add_u32 v143, v0, 4, v2
	v_and_b32_e32 v2, 31, v177
	v_mov_b32_e32 v135, 0
	v_or3_b32 v3, v3, v7, v6
	s_and_b64 s[0:1], s[8:9], exec
	v_lshlrev_b32_e32 v134, 4, v176
	v_mul_u32_u24_e32 v174, 0x90, v3
	v_mul_u32_u24_e32 v180, 0x50, v2
	v_lshl_add_u64 v[2:3], s[80:81], 0, v[134:135]
	s_mov_b64 s[0:1], 0x1b700000
	v_lshl_add_u64 v[144:145], v[2:3], 0, s[0:1]
	v_lshrrev_b32_e32 v2, 3, v4
	s_mov_b32 s0, 0xfffffc
	v_lshlrev_b32_e32 v3, 3, v4
	v_lshrrev_b32_e32 v5, 5, v176
	v_bfe_u32 v170, v177, 2, 3
	v_lshlrev_b32_e32 v136, 3, v0
	v_cndmask_b32_e64 v7, v1, v143, s[8:9]
	v_lshlrev_b64 v[0:1], v176, -1
	v_and_or_b32 v2, v2, s0, v141
	v_and_b32_e32 v3, 0xf8, v3
	v_lshlrev_b32_e32 v132, 3, v5
	v_mov_b32_e32 v8, 0xf00
	v_lshlrev_b32_e32 v179, 7, v5
	v_not_b32_e32 v133, v1
	v_lshlrev_b32_e32 v1, 4, v170
	v_lshl_or_b32 v146, v2, 8, v3
	v_or_b32_e32 v3, s3, v170
	v_lshl_or_b32 v8, v177, 2, v8
	v_lshlrev_b32_e32 v175, 4, v5
	v_lshlrev_b32_e32 v138, 5, v4
	v_lshlrev_b32_e32 v6, 1, v5
	s_cselect_b32 s97, 7, 12
	v_not_b32_e32 v142, v0
	s_add_u32 s46, s80, 0x31fb100
	v_lshlrev_b32_e32 v0, 3, v176
	v_lshlrev_b32_e32 v2, 2, v5
	v_sub_u32_e32 v4, v3, v179
	v_sub_u32_e32 v3, v3, v132
	s_mov_b32 s54, 2.0
	v_add_u32_e32 v189, s51, v1
	s_mov_b32 s60, 4.0
	s_mov_b32 s62, 0x40c00000
	s_mov_b32 s64, 0x41800000
	s_mov_b32 s66, 0x41900000
	s_mov_b32 s68, 0x41a00000
	s_mov_b32 s82, 0x41b00000
	v_mbcnt_lo_u32_b32 v1, -1, 0
	s_mov_b32 s31, 0
	v_lshl_add_u32 v171, v176, 2, s51
	v_or_b32_e32 v172, 64, v176
	v_add_u32_e32 v173, s51, v8
	v_cmp_eq_u32_e64 s[4:5], 0, v176
	v_add3_u32 v178, s95, v174, v175
	v_ashrrev_i32_e32 v139, 31, v138
	v_lshlrev_b32_e32 v140, 3, v141
	v_cmp_eq_u32_e64 s[6:7], 0, v141
	s_addc_u32 s47, s81, 0
	v_ashrrev_i32_e32 v147, 31, v146
	v_add_u32_e32 v181, s95, v7
	v_add_u32_e32 v182, 0xfffffe71, v4
	v_add_u32_e32 v183, 32, v137
	v_lshl_or_b32 v184, v170, 7, v6
	v_xor_b32_e32 v185, 0x7a, v6
	s_add_i32 s33, s51, 0x2000
	v_subrev_u32_e32 v186, 33, v3
	s_mov_b64 s[48:49], 0
	s_add_i32 s26, 0, 0x15c00
	s_mov_b32 s30, 0xf800000
	v_mov_b32_e32 v187, 0x260
	s_mov_b32 s50, 0x3e38aa3b
	s_mov_b32 s53, 0x3fb8aa3b
	s_mov_b32 s55, 0x40400000
	v_mov_b32_e32 v188, 0xc1f80000
	s_movk_i32 s28, 0x200
	s_mov_b32 s61, 0x40a00000
	s_mov_b32 s63, 0x40e00000
	s_mov_b32 s65, 0x41880000
	s_mov_b32 s67, 0x41980000
	s_mov_b32 s69, 0x41a80000
	s_mov_b32 s83, 0x41b80000
	s_mov_b32 s29, 0xf149f2ca
	s_mov_b32 s27, 0x41000000
	s_mov_b64 s[84:85], 0xe00
	v_lshlrev_b32_e32 v148, 1, v2
	v_mov_b32_e32 v190, 0x42800000
	v_not_b32_e32 v191, 63
	v_mbcnt_hi_u32_b32 v192, -1, v1
	v_mov_b32_e32 v193, 0x2600
	v_mov_b32_e32 v150, 0x3e38aa3b
	v_mov_b32_e32 v194, 0xff800000
	v_lshlrev_b32_e32 v152, 1, v0
	v_mov_b32_e32 v154, 1.0
	v_writelane_b32 v246, s3, 39
	s_mov_b64 s[0:1], exec
	v_readlane_b32 s2, v247, 13
	v_readlane_b32 s3, v247, 14
	s_and_b64 s[2:3], s[0:1], s[2:3]
	s_mov_b64 exec, s[2:3]
	s_cbranch_execz .Lnsa_q_pre_done
	v_readlane_b32 s10, v246, 43
	v_readlane_b32 s11, v246, 44
	v_mov_b32_e32 v245, 1
	s_nop 4
	global_atomic_add v245, v135, v245, s[10:11] sc0
.Lnsa_q_pre_done:
	s_mov_b64 exec, s[0:1]
	s_branch .LBB0_967

; DI float bf2f(bf16_t v) { return __uint_as_float((unsigned)v << 16); }
; DI void wave_lds_sync() { asm volatile("s_waitcnt lgkmcnt(0)" ::: "memory"); }
; DI void nsa_block(const bf16_t* P1, const bf16_t* VT1, const bf16_t* KSF, const bf16_t* KC, const bf16_t* VCT, bf16_t* O, const unsigned* kmx, int b, int g, int t0b, int wave, int lane, unsigned char* lds) {
;     ...
;     const bf16_t* prow = P1 + (size_t)(b * S_ + t) * LDP1;
;     bf16x8 qf[4];
; #pragma unroll
;     for (int ks = 0; ks < 4; ++ks) qf[ks] = ldg8(prow + head * 64 + 8 * hf + 16 * ks);
;     const float gc = 1.f / (1.f + __expf(-bf2f(prow[2048 + head * 3 + 0]))), gs = 1.f / (1.f + __expf(-bf2f(prow[2048 + head * 3 + 1]))), gwn = 1.f / (1.f + __expf(-bf2f(prow[2048 + head * 3 + 2])));
; #pragma unroll
;     for (int i = 0; i < 16; ++i) { impA[lane + 64 * i] = 0.f; impB[lane + 64 * i] = 0.f; }
;     wave_lds_sync();
;     const int nmax = tmax >= 31 ? ((tmax - 31) >> 4) + 1 : 0, ntile = (nmax + 31) >> 5;
;     const bf16_t* kcb = KC + (size_t)((b * 4 + g) * 512) * 64;
;     const bf16_t* vcb = VCT + (size_t)((b * 4 + g) * 64) * 512;
;     int lo_b = 0, lo_w = 0;
;     { float qq = 0.f;
; #pragma unroll
;       for (int ks = 0; ks < 4; ++ks)
; #pragma unroll
;           for (int e = 0; e < 8; ++e) { const float v = bf2f((bf16_t)qf[ks][e]); qq += v * v; }
;       qq += __shfl_xor(qq, 32);
;     ...
;     for (;;) {
;         if (threadIdx.x == 0) qidx[0] = atomicAdd(qctr, 1u);
;         __syncthreads();
;         const unsigned idx = qidx[0];
;         __syncthreads();
;         if (idx >= 2048u) break;
;         const int bg = idx & 15, tile = 127 - (int)(idx >> 4);
;         nsa_block(P1, VT1, (const bf16_t*)(p.ws + WS_KSF), KC, VCT, O, (const unsigned*)(p.ws + WS_KMX), bg >> 2, bg & 3, tile * 64, wave, lane, lds);
.LBB0_967:
	s_mov_b64 s[0:1], exec
	v_readlane_b32 s2, v247, 13
	v_readlane_b32 s3, v247, 14
	s_and_b64 s[2:3], s[0:1], s[2:3]
	s_mov_b64 exec, s[2:3]
	s_cbranch_execz .LBB0_971
	s_mov_b64 s[10:11], exec
	v_mbcnt_lo_u32_b32 v0, s10, 0
	v_mbcnt_hi_u32_b32 v0, s11, v0
	v_cmp_eq_u32_e32 vcc, 0, v0
	s_and_saveexec_b64 s[2:3], vcc
	s_cbranch_execz .LBB0_970
	v_readlane_b32 s10, v246, 43
	v_readlane_b32 s11, v246, 44
	s_waitcnt vmcnt(0)
	v_mov_b32_e32 v1, v245
	v_mov_b32_e32 v245, 1
	s_nop 4
	global_atomic_add v245, v135, v245, s[10:11] sc0
.LBB0_970:
	s_or_b64 exec, exec, s[2:3]
	v_readfirstlane_b32 s2, v1
	s_nop 3
	v_add_u32_e32 v2, s2, v0
	v_mov_b32_e32 v0, s26
	ds_write_b32 v0, v2
.LBB0_971:
	s_or_b64 exec, exec, s[0:1]
	v_mov_b32_e32 v0, s26
	s_waitcnt lgkmcnt(0)
	s_barrier
	ds_read_b32 v0, v0
	s_movk_i32 s0, 0x800
	s_waitcnt lgkmcnt(0)
	s_barrier
	v_cmp_gt_u32_e32 vcc, s0, v0
	s_mov_b64 s[0:1], -1
	s_and_saveexec_b64 s[86:87], vcc
	s_cbranch_execz .LBB0_966
	v_not_b32_e32 v1, v0
	v_lshlrev_b32_e32 v1, 2, v1
	v_and_b32_e32 v166, 0x1fc0, v1
	v_readlane_b32 s0, v246, 39
	v_bfe_u32 v162, v0, 2, 2
	v_and_b32_e32 v161, 3, v0
	v_add_u32_e32 v149, s0, v166
	v_or_b32_e32 v155, v149, v170
	v_lshl_or_b32 v24, v161, 2, v141
	v_lshl_add_u32 v134, v162, 13, v155
	v_mov_b64_e32 v[2:3], s[38:39]
	v_mad_u64_u32 v[2:3], s[0:1], v134, s96, v[2:3]
	v_lshlrev_b32_e32 v4, 7, v24
	v_mov_b32_e32 v5, v135
	v_lshl_add_u64 v[4:5], v[2:3], 0, v[4:5]
	v_lshlrev_b32_e32 v6, 1, v132
	v_mov_b32_e32 v7, v135
	v_lshl_add_u64 v[4:5], v[4:5], 0, v[6:7]
	global_load_dwordx4 v[112:115], v[4:5], off
	global_load_dwordx4 v[116:119], v[4:5], off offset:32
	global_load_dwordx4 v[120:123], v[4:5], off offset:64
	global_load_dwordx4 v[124:127], v[4:5], off offset:96
	v_and_b32_e32 v25, 15, v0
	v_add_u32_e32 v0, 1, v24
	v_mul_u32_u24_e32 v5, 3, v24
	v_mov_b32_e32 v1, v135
	v_cvt_f32_ubyte0_e32 v12, v0
	v_lshlrev_b32_e32 v0, 1, v5
	s_mov_b64 s[0:1], 0x1000
	s_movk_i32 s2, 0x1000
	v_lshl_add_u64 v[0:1], v[2:3], 0, v[0:1]
	v_lshl_add_u64 v[2:3], v[0:1], 0, s[0:1]
	v_add_co_u32_e32 v0, vcc, s2, v0
	ds_write2st64_b32 v171, v135, v135 offset1:1
	ds_write2st64_b32 v171, v135, v135 offset0:17 offset1:18
	ds_write2st64_b32 v171, v135, v135 offset0:2 offset1:3
	ds_write2st64_b32 v171, v135, v135 offset0:19 offset1:20
	ds_write2st64_b32 v171, v135, v135 offset0:4 offset1:5
	ds_write2st64_b32 v171, v135, v135 offset0:21 offset1:22
	ds_write2st64_b32 v171, v135, v135 offset0:6 offset1:7
	ds_write2st64_b32 v171, v135, v135 offset0:23 offset1:24
	ds_write2st64_b32 v171, v135, v135 offset0:8 offset1:9
	ds_write2st64_b32 v171, v135, v135 offset0:25 offset1:26
	ds_write2st64_b32 v171, v135, v135 offset0:10 offset1:11
	ds_write2st64_b32 v171, v135, v135 offset0:27 offset1:28
	ds_write2st64_b32 v171, v135, v135 offset0:12 offset1:13
	ds_write2st64_b32 v171, v135, v135 offset0:14 offset1:16
	ds_write2st64_b32 v171, v135, v135 offset0:29 offset1:30
	ds_write2st64_b32 v173, v135, v135 offset1:16
	v_addc_co_u32_e32 v1, vcc, 0, v1, vcc
	v_lshlrev_b32_e32 v4, 3, v25
	global_load_dword v158, v[0:1], off
	global_load_ushort v160, v[2:3], off offset:4
	s_waitcnt lgkmcnt(0)
	global_load_dword v53, v4, s[36:37] sc1
	global_load_dword v1, v4, s[36:37] offset:4 sc1
	v_mul_f32_e32 v13, -0.5, v12
	s_mov_b32 s0, 0xc2fc0000
	s_mov_b32 s52, s54
	v_subrev_u32_e32 v54, 31, v155
	s_waitcnt vmcnt(7)
	v_and_b32_e32 v10, 0xffff0000, v112
	v_lshlrev_b32_e32 v0, 16, v112
	v_mul_f32_e32 v10, v10, v10
	v_lshlrev_b32_e32 v14, 16, v113
	v_fmac_f32_e32 v10, v0, v0
	v_and_b32_e32 v15, 0xffff0000, v113
	v_fmac_f32_e32 v10, v14, v14
	v_lshlrev_b32_e32 v16, 16, v114
	v_fmac_f32_e32 v10, v15, v15
	v_and_b32_e32 v17, 0xffff0000, v114
	v_fmac_f32_e32 v10, v16, v16
	v_lshlrev_b32_e32 v18, 16, v115
	v_fmac_f32_e32 v10, v17, v17
	v_and_b32_e32 v19, 0xffff0000, v115
	v_fmac_f32_e32 v10, v18, v18
	s_waitcnt vmcnt(6)
	v_lshlrev_b32_e32 v20, 16, v116
	v_fmac_f32_e32 v10, v19, v19
	v_and_b32_e32 v21, 0xffff0000, v116
	v_fmac_f32_e32 v10, v20, v20
	v_lshlrev_b32_e32 v22, 16, v117
	v_fmac_f32_e32 v10, v21, v21
	v_and_b32_e32 v23, 0xffff0000, v117
	v_fmac_f32_e32 v10, v22, v22
	v_lshlrev_b32_e32 v26, 16, v118
	v_fmac_f32_e32 v10, v23, v23
	v_and_b32_e32 v27, 0xffff0000, v118
	v_fmac_f32_e32 v10, v26, v26
	v_lshlrev_b32_e32 v28, 16, v119
	v_fmac_f32_e32 v10, v27, v27
	v_and_b32_e32 v29, 0xffff0000, v119
	v_fmac_f32_e32 v10, v28, v28
	s_waitcnt vmcnt(5)
; DI float bf2f(bf16_t v) { return __uint_as_float((unsigned)v << 16); }
; DI void nsa_block(const bf16_t* P1, const bf16_t* VT1, const bf16_t* KSF, const bf16_t* KC, const bf16_t* VCT, bf16_t* O, const unsigned* kmx, int b, int g, int t0b, int wave, int lane, unsigned char* lds) {
;     ...
;     { float qq = 0.f;
; #pragma unroll
;       for (int ks = 0; ks < 4; ++ks)
; #pragma unroll
;           for (int e = 0; e < 8; ++e) { const float v = bf2f((bf16_t)qf[ks][e]); qq += v * v; }
;       qq += __shfl_xor(qq, 32);
;       const unsigned* kcm = kmx + 96 + (b * 4 + g) * 2;
;       const float kc2 = __uint_as_float(__hip_atomic_load(kcm, __ATOMIC_RELAXED, __HIP_MEMORY_SCOPE_AGENT)) + __uint_as_float(__hip_atomic_load(kcm + 1, __ATOMIC_RELAXED, __HIP_MEMORY_SCOPE_AGENT));
;       const float ubc = sqrtf(qq * kc2 * 1.02f) * C1;
;       const float Dcol = (150.f + 2.f * ubc) / slope2 + 15.f;
;       const float f = (((float)(t - 31) - Dcol) * (1.f / 16.f) - 31.f) * (1.f / 32.f);
;       int lo = f > 0.f ? (int)floorf(f) : 0;
; #pragma unroll
;       for (int o = 1; o < 64; o <<= 1) lo = min(lo, __shfl_xor(lo, o));
;       lo_w = lo;
;       volatile int* xl = (volatile int*)(SB + 2 * NS_BUF + 64);
;       if (lane == 0) xl[wave] = lo_w;
	v_lshlrev_b32_e32 v30, 16, v120
	v_fmac_f32_e32 v10, v29, v29
	v_and_b32_e32 v31, 0xffff0000, v120
	v_fmac_f32_e32 v10, v30, v30
	v_lshlrev_b32_e32 v32, 16, v121
	v_fmac_f32_e32 v10, v31, v31
	v_and_b32_e32 v33, 0xffff0000, v121
	v_and_b32_e32 v3, 0xffff0000, v122
	v_lshlrev_b32_e32 v2, 16, v122
	v_fmac_f32_e32 v10, v32, v32
	v_pk_mul_f32 v[2:3], v[2:3], v[2:3]
	v_fmac_f32_e32 v10, v33, v33
	v_and_b32_e32 v5, 0xffff0000, v123
	v_lshlrev_b32_e32 v4, 16, v123
	v_add_f32_e32 v0, v2, v10
	v_pk_mul_f32 v[4:5], v[4:5], v[4:5]
	v_add_f32_e32 v0, v3, v0
	s_waitcnt vmcnt(4)
	v_and_b32_e32 v7, 0xffff0000, v124
	v_lshlrev_b32_e32 v6, 16, v124
	v_add_f32_e32 v0, v4, v0
	v_pk_mul_f32 v[6:7], v[6:7], v[6:7]
	v_add_f32_e32 v0, v5, v0
	v_and_b32_e32 v9, 0xffff0000, v125
	v_lshlrev_b32_e32 v8, 16, v125
	v_add_f32_e32 v0, v6, v0
	v_pk_mul_f32 v[8:9], v[8:9], v[8:9]
	v_add_f32_e32 v0, v7, v0
	v_and_b32_e32 v11, 0xffff0000, v126
	v_add_f32_e32 v0, v8, v0
	v_lshlrev_b32_e32 v10, 16, v126
	v_add_f32_e32 v0, v9, v0
	v_pk_mul_f32 v[2:3], v[10:11], v[10:11]
	s_nop 0
	v_add_f32_e32 v0, v2, v0
	v_add_f32_e32 v0, v3, v0
	v_and_b32_e32 v3, 0xffff0000, v127
	v_lshlrev_b32_e32 v2, 16, v127
	v_pk_mul_f32 v[2:3], v[2:3], v[2:3]
	s_nop 0
	v_add_f32_e32 v0, v2, v0
	v_and_b32_e32 v2, 64, v192
	v_add_f32_e32 v52, v3, v0
	v_xor_b32_e32 v0, 32, v192
	v_add_u32_e32 v2, 64, v2
	v_cmp_lt_i32_e32 vcc, v0, v2
	s_nop 1
	v_cndmask_b32_e32 v0, v192, v0, vcc
	v_lshlrev_b32_e32 v195, 2, v0
	ds_bpermute_b32 v0, v195, v52
	v_cmp_gt_f32_e32 vcc, s0, v13
	s_waitcnt vmcnt(0) lgkmcnt(0)
	v_pk_add_f32 v[0:1], v[52:53], v[0:1]
	s_nop 0
	v_mul_f32_e32 v0, v0, v1
	v_mul_f32_e32 v0, 0x3f828f5c, v0
	v_cndmask_b32_e32 v3, 0, v190, vcc
	v_mul_f32_e32 v1, 0x4f800000, v0
	v_cmp_gt_f32_e64 s[0:1], s30, v0
	v_fmac_f32_e32 v3, -0.5, v12
	v_exp_f32_e32 v3, v3
	v_cndmask_b32_e64 v0, v0, v1, s[0:1]
	v_sqrt_f32_e32 v4, v0
	v_cndmask_b32_e32 v1, 0, v191, vcc
	v_ldexp_f32 v1, v3, v1
	v_add_u32_e32 v3, -1, v4
	v_fma_f32 v5, -v3, v4, v0
	v_cmp_ge_f32_e32 vcc, 0, v5
	v_add_u32_e32 v5, 1, v4
	s_nop 0
	v_cndmask_b32_e32 v3, v4, v3, vcc
	v_fma_f32 v4, -v5, v4, v0
	v_cmp_lt_f32_e32 vcc, 0, v4
	s_nop 1
	v_cndmask_b32_e32 v3, v3, v5, vcc
	v_mul_f32_e32 v4, 0x37800000, v3
	v_cndmask_b32_e64 v3, v3, v4, s[0:1]
	v_cmp_class_f32_e32 vcc, v0, v187
	s_nop 1
	v_cndmask_b32_e32 v0, v3, v0, vcc
	v_mul_f32_e32 v0, 0x3e38aa3b, v0
	v_pk_mul_f32 v[156:157], v[0:1], s[52:53]
	s_nop 0
	v_add_f32_e32 v0, 0x43160000, v156
	v_div_scale_f32 v1, s[0:1], v157, v157, v0
	v_rcp_f32_e32 v3, v1
	s_nop 0
	v_fma_f32 v4, -v1, v3, 1.0
	v_fmac_f32_e32 v3, v4, v3
	v_div_scale_f32 v4, vcc, v0, v157, v0
	v_mul_f32_e32 v5, v4, v3
	v_fma_f32 v6, -v1, v5, v4
	v_fmac_f32_e32 v5, v6, v3
	v_fma_f32 v1, -v1, v5, v4
	v_cvt_f32_i32_e32 v4, v54
	v_div_fmas_f32 v1, v1, v3, v5
	v_div_fixup_f32 v0, v1, v157, v0
	v_add_f32_e32 v0, 0x41700000, v0
	v_sub_f32_e32 v0, v4, v0
	v_fmamk_f32 v0, v0, 0x3d800000, v188
	v_mul_f32_e32 v0, 0x3d000000, v0
	v_floor_f32_e32 v1, v0
	v_cvt_i32_f32_e32 v1, v1
	v_cmp_lt_f32_e32 vcc, 0, v0
	s_nop 1
	v_cndmask_b32_e32 v0, 0, v1, vcc
	v_xor_b32_e32 v1, 1, v192
	v_cmp_lt_i32_e32 vcc, v1, v2
	s_nop 1
	v_cndmask_b32_e32 v1, v192, v1, vcc
	v_lshlrev_b32_e32 v55, 2, v1
	ds_bpermute_b32 v1, v55, v0
	s_waitcnt lgkmcnt(0)
	v_min_i32_e32 v0, v0, v1
	v_xor_b32_e32 v1, 2, v192
	v_cmp_lt_i32_e32 vcc, v1, v2
	s_nop 1
	v_cndmask_b32_e32 v1, v192, v1, vcc
	v_lshlrev_b32_e32 v59, 2, v1
	ds_bpermute_b32 v1, v59, v0
	s_waitcnt lgkmcnt(0)
	v_min_i32_e32 v0, v0, v1
	v_xor_b32_e32 v1, 4, v192
	v_cmp_lt_i32_e32 vcc, v1, v2
	s_nop 1
	v_cndmask_b32_e32 v1, v192, v1, vcc
	v_lshlrev_b32_e32 v1, 2, v1
	ds_bpermute_b32 v1, v1, v0
	s_waitcnt lgkmcnt(0)
	v_min_i32_e32 v0, v0, v1
	v_xor_b32_e32 v1, 8, v192
	v_cmp_lt_i32_e32 vcc, v1, v2
	s_nop 1
	v_cndmask_b32_e32 v1, v192, v1, vcc
	v_lshlrev_b32_e32 v1, 2, v1
	ds_bpermute_b32 v1, v1, v0
	s_waitcnt lgkmcnt(0)
	v_min_i32_e32 v0, v0, v1
	v_xor_b32_e32 v1, 16, v192
	v_cmp_lt_i32_e32 vcc, v1, v2
	s_nop 1
	v_cndmask_b32_e32 v1, v192, v1, vcc
	v_lshlrev_b32_e32 v1, 2, v1
	ds_bpermute_b32 v1, v1, v0
	s_waitcnt lgkmcnt(0)
	v_min_i32_e32 v0, v0, v1
	ds_bpermute_b32 v1, v195, v0
	s_waitcnt lgkmcnt(0)
	v_min_i32_e32 v64, v0, v1
	s_and_saveexec_b64 s[0:1], s[4:5]
	s_cbranch_execz .LBB0_974
	v_mov_b64_e32 v[0:1], s[22:23]
	flat_store_dword v[0:1], v64 sc0 sc1
	s_waitcnt vmcnt(0)
